# P7: first two DMA waits of each unit's (peeled) first K-iteration relaxed to vmcnt(26) so the epilogue's ACT stores need not retire before the K-loop restarts (in-order vmcnt); full wait after the pha
# baseline (speedup 1.0000x reference)
; #define PG8_LAS __attribute__((address_space(3)))
; #define PG8_STAGE(bufoff, gbase, voff) do { _Pragma("unroll") for (int _i = 0; _i < 2; ++_i) \
;         __builtin_amdgcn_global_load_lds((const unsigned*)((const char*)(gbase) + (voff)[_i]), (PG8_LAS unsigned*)(lds + (bufoff) + ldsw + _i * 8192), 16, 0, 0); } while (0)
; #define PG8_WAIT_V(n) asm volatile("s_waitcnt vmcnt(" #n ")" ::: "memory")
; #define PG8_BAR __builtin_amdgcn_s_barrier()
;     __device__ __forceinline__ void operator()(const f32x4 (&acc)[2][2][4][2], const Unit& u, int wr, int wc, int fr, int fq) const {
;         constexpr int FF = 2816, FF2 = 5632;
;         const int lcol = wc * 32 + 8 * fq, gcol = u.pn * HALF + lcol;
;         float rs[2][4];
;         load_rs(slots, u.pm * BM + wr * 64, fr, fq, 1.0f, rs);
;         if (fr >= 14) {
; #pragma unroll
;             for (int ai = 0; ai < 2; ++ai)
; #pragma unroll
;                 for (int bj = 0; bj < 2; ++bj)
; #pragma unroll
;                     for (int n = 0; n < 2; ++n) { const f32x4 x = acc[ai][bj][3][n] * rs[ai][3];
;                         *(PG8_LAS f32x4*)(halo + ((ai * 2 + wr) * 2 + (fr - 14)) * 256 + bj * HALF + lcol + 4 * n) = x;
; template <class Epi, class Sched, bool ALIGN_EPI = false, bool SP2 = false>
; __device__ __forceinline__ void gemm_phase(PG8_LAS unsigned char* lds, const Gemm g, const Sched& S, const Epi& E, int wave_in) {
;     ...
;         PG8_STAGE(PG8_SB(0, 0), cB, voffB); PG8_STAGE(PG8_SB(0, 1), cB + hstep, voffB); PG8_STAGE(PG8_SA(0, 0), cA, voffA); PG8_STAGE(PG8_SA(0, 1), cA + hstep, voffA);
;         if (wr == 1) PG8_BAR;
;         PG8_WAIT_V(2); PG8_BAR;
;         PG8_STAGE(PG8_SB(1, 0), cB + kstep, voffB); PG8_STAGE(PG8_SA(1, 0), cA + kstep, voffA); PG8_STAGE(PG8_SB(1, 1), cB + hstep + kstep, voffB);
;         PG8_WAIT_V(6); PG8_BAR;
.LBB0_891:
	s_add_u32 s24, s22, 0xf100000
	s_addc_u32 s25, s23, 0
	s_add_u32 s26, s12, 0x5500000
	s_addc_u32 s27, s13, 0
	v_readlane_b32 s12, v255, 37
	s_mul_i32 s8, s12, 0x5800
	s_add_u32 s60, s50, s8
	s_addc_u32 s61, s51, 0
	s_add_u32 s10, s10, 0x5900000
	s_addc_u32 s11, s11, 0
	s_add_u32 s84, s4, 0x6500000
	s_addc_u32 s85, s5, 0
	s_add_u32 s92, s14, 0xb000
	v_readlane_b32 s13, v255, 38
	v_writelane_b32 v255, s10, 37
	s_addc_u32 s93, s15, 0
	s_lshl_b32 s4, s9, 5
	v_writelane_b32 v255, s11, 38
	s_and_b32 s11, s4, 0x60
	s_add_i32 m0, s33, 0x18000
	v_lshl_add_u64 v[6:7], v[6:7], 0, s[88:89]
	s_lshl_b32 s8, s18, 6
	s_lshl_b32 s10, s18, 13
	s_lshl_b32 s12, s11, 7
	s_waitcnt vmcnt(2)
	s_barrier
	global_load_lds_dwordx4 v[6:7], off
	v_lshl_add_u64 v[4:5], v[4:5], 0, s[88:89]
	s_add_i32 m0, s33, 0x1a000
	s_add_i32 s9, s33, 0x8000
	s_add_i32 s96, s33, 0xa000
	global_load_lds_dwordx4 v[4:5], off
	v_lshl_add_u64 v[2:3], v[2:3], 0, s[88:89]
	s_mov_b32 m0, s9
	s_add_u32 s4, s78, 0x40080
	global_load_lds_dwordx4 v[2:3], off
	v_lshl_add_u64 v[0:1], v[0:1], 0, s[88:89]
	s_mov_b32 m0, s96
	s_addc_u32 s5, s79, 0
	global_load_lds_dwordx4 v[0:1], off
	s_add_i32 m0, s33, 0x1c000
	v_lshl_add_u64 v[0:1], s[4:5], 0, v[192:193]
	global_load_lds_dwordx4 v[0:1], off
	v_lshl_add_u64 v[0:1], s[4:5], 0, v[168:169]
	s_add_i32 m0, s33, 0x1e000
	v_and_b32_e32 v206, 15, v8
	global_load_lds_dwordx4 v[0:1], off
	v_bfe_u32 v0, v8, 4, 2
	v_lshlrev_b32_e32 v1, 4, v0
	v_lshlrev_b32_e32 v2, 2, v8
	v_lshl_or_b32 v1, v206, 6, v1
	v_and_b32_e32 v2, 32, v2
	s_cmpk_lt_u32 s19, 0x100
	v_bitop3_b32 v3, v1, s10, v2 bitop3:0xde
	s_cselect_b64 s[94:95], -1, 0
	s_lshl_b32 s10, s18, 11
	s_cmp_gt_i32 s18, 0
	v_cmp_lt_u32_e32 vcc, 13, v206
	v_cmp_gt_u32_e64 s[46:47], 2, v206
	s_cselect_b64 s[4:5], -1, 0
	v_bitop3_b32 v207, v1, s12, v2 bitop3:0xde
	s_and_b64 s[22:23], vcc, s[4:5]
	s_and_b64 s[12:13], s[94:95], s[46:47]
	s_cmp_gt_i32 s18, -2
	s_cselect_b64 s[4:5], -1, 0
	v_lshl_or_b32 v208, v0, 3, s11
	v_add_u32_e32 v210, -14, v206
	s_and_b64 s[82:83], vcc, s[4:5]
	s_add_i32 s4, s10, 0x100
	v_lshlrev_b32_e32 v0, 10, v210
	v_lshlrev_b32_e32 v1, 10, v206
	s_add_i32 s5, s4, 0x22000
	v_lshlrev_b32_e32 v2, 2, v208
	s_add_i32 s4, s4, 0x23000
	v_add3_u32 v211, s5, v0, v2
	v_add3_u32 v212, s4, v0, v2
	v_add3_u32 v0, s5, v1, v2
	v_add_u32_e32 v213, 0xffffc000, v0
	v_add_u32_e32 v214, 0xffffd000, v0
	v_add_u32_e32 v215, 0xffffc010, v0
	v_add_u32_e32 v216, 0xffffc210, v0
	v_add_u32_e32 v217, 0xffffd010, v0
	v_add_u32_e32 v218, 0xffffd210, v0
	v_lshlrev_b32_e32 v0, 14, v9
	v_and_b32_e32 v0, 0xffff8000, v0
	v_lshl_add_u32 v0, v10, 11, v0
	v_and_b32_e32 v1, 1, v9
	v_lshl_or_b32 v0, v1, 6, v0
	v_lshl_add_u32 v174, v11, 1, v0
	v_lshlrev_b32_e32 v0, 14, v13
	v_and_b32_e32 v0, 0xffff8000, v0
	s_waitcnt vmcnt(6)
	v_lshl_add_u32 v0, v12, 11, v0
	v_and_b32_e32 v1, 1, v13
	v_lshl_or_b32 v0, v1, 6, v0
	v_readlane_b32 s4, v255, 10
	v_and_b32_e32 v209, 63, v8
	v_cmp_gt_u32_e64 s[40:41], 14, v206
	s_mov_b32 s97, 0
	v_cmp_eq_u32_e64 s[42:43], 0, v206
	v_cmp_lt_u32_e64 s[44:45], 1, v206
	v_mov_b32_e32 v175, v193
	v_lshl_add_u32 v176, v14, 1, v0
	v_mov_b32_e32 v177, v193
	v_add_u32_e32 v219, 0x100, v3
	v_readlane_b32 s69, v254, 57
	s_mov_b32 s71, s4
	s_barrier
	v_readlane_b32 s5, v255, 11
	s_waitcnt vmcnt(0)
	s_mov_b32 s101, -1
	s_branch .LBB0_894

; #define PG8_STAGE(bufoff, gbase, voff) do { _Pragma("unroll") for (int _i = 0; _i < 2; ++_i) \
;         __builtin_amdgcn_global_load_lds((const unsigned*)((const char*)(gbase) + (voff)[_i]), (PG8_LAS unsigned*)(lds + (bufoff) + ldsw + _i * 8192), 16, 0, 0); } while (0)
; #define PG8_LDA(dst, b, h) do { _Pragma("unroll") for (int m = 0; m < 4; ++m) _Pragma("unroll") for (int k = 0; k < 2; ++k) dst[m][k] = *(const PG8_LAS bf16x8*)(lds + PG8_SA(b, h) + aoff + m * 2048 + k * 1024); } while (0)
; #define PG8_LDB(dst, b, h) do { _Pragma("unroll") for (int n = 0; n < 2; ++n) _Pragma("unroll") for (int k = 0; k < 2; ++k) dst[n][k] = *(const PG8_LAS bf16x8*)(lds + PG8_SB(b, h) + boff + n * 2048 + k * 1024); } while (0)
; #define PG8_WAIT_V(n) asm volatile("s_waitcnt vmcnt(" #n ")" ::: "memory")
; #define PG8_WAIT_L(n) asm volatile("s_waitcnt lgkmcnt(" #n ")" ::: "memory")
; #define PG8_BAR __builtin_amdgcn_s_barrier()
; template <class Epi, class Sched, bool ALIGN_EPI = false, bool SP2 = false>
; __device__ __forceinline__ void gemm_phase(PG8_LAS unsigned char* lds, const Gemm g, const Sched& S, const Epi& E, int wave_in) {
;     ...
;         const bool has_next = S.next(ui + 1, nxt);
;         const char* nA = has_next ? (const char*)g.A + (size_t)(nxt.pm >> g.ash) * g.astride + (size_t)nxt.pm * tstep : cA; const char* nB = has_next ? (const char*)g.Bt + (size_t)(nxt.pm >> g.bsh) * g.bstride + (size_t)nxt.pn * tstep : cB;
;         for (int t = 0; t < nt; t += 2) {
;             const bool last = (t == nt - 2);
;             const char* a1 = cA + (size_t)(t + 1) * kstep;
;             const char* a2 = last ? nA : cA + (size_t)(t + 2) * kstep; const char* b2 = last ? nB : cB + (size_t)(t + 2) * kstep;
;             const char* a3 = a2 + kstep; const char* b3 = b2 + kstep;
;             if (last && has_next) S.a_ready(nxt);
;             if constexpr (SP2) {
;             PG8_LDB(B0, 0, 0); PG8_LDB(B1, 0, 1); PG8_SCHED; PG8_LDA(At, 0, 0); PG8_STAGE(PG8_SA(1, 1), a1 + hstep, voffA);
;             PG8_WAIT_V(8); PG8_WAIT_L(0); PG8_BAR; PG8_MMA(0, 0, At, B0); PG8_MMA(0, 1, At, B1); PG8_BAR; PG8_SCHED;
;             PG8_LDA(At, 0, 1); PG8_STAGE(PG8_SB(0, 0), b2, voffB); PG8_STAGE(PG8_SB(0, 1), b2 + hstep, voffB); PG8_STAGE(PG8_SA(0, 0), a2, voffA);
;             PG8_WAIT_V(8); PG8_WAIT_L(0); PG8_BAR; PG8_MMA(1, 0, At, B0); PG8_MMA(1, 1, At, B1); PG8_BAR; PG8_SCHED;
.LBB0_896:
	s_ashr_i32 s11, s10, 31
	s_lshl_b64 s[18:19], s[10:11], 19
	s_add_u32 s66, s6, s18
	s_addc_u32 s67, s72, s19
	s_and_b64 s[18:19], s[46:47], exec
	s_cselect_b32 s11, s67, s1
	s_cselect_b32 s34, s66, s0
	s_ashr_i32 s5, s4, 31
	s_lshl_b64 s[18:19], s[4:5], 19
	s_add_u32 s38, s73, s18
	s_addc_u32 s39, s74, s19
	s_and_b64 s[18:19], s[46:47], exec
	s_cselect_b32 s5, s39, s79
	s_cselect_b32 s53, s38, s78
	s_add_u32 s81, s78, 0x100
	s_addc_u32 s18, s79, 0
	s_add_u32 vcc_lo, s0, 0x40080
	s_addc_u32 vcc_hi, s1, 0
	s_mov_b32 s19, -2
	s_add_u32 s0, vcc_lo, 0xfffc0080
	s_addc_u32 s1, vcc_hi, -1
	s_add_i32 s76, s35, 0x100
	s_cmp_eq_u32 s19, 12
	s_cselect_b32 s79, s11, s1
	s_cselect_b32 s78, s34, s0
	s_cselect_b32 s1, s5, s18
	s_cselect_b32 s0, s53, s81
	s_add_i32 s29, s90, 0x100
	v_add_u32_e32 v140, s76, v207
	v_add_u32_e32 v156, s29, v207
	ds_read_b128 v[128:131], v140
	ds_read_b128 v[132:135], v140 offset:1024
	ds_read_b128 v[136:139], v140 offset:2048
	ds_read_b128 v[140:143], v140 offset:3072
	ds_read_b128 v[144:147], v156
	ds_read_b128 v[148:151], v156 offset:1024
	ds_read_b128 v[152:155], v156 offset:2048
	ds_read_b128 v[156:159], v156 offset:3072
	v_lshl_add_u64 v[190:191], vcc, 0, v[176:177]
	s_add_i32 m0, s33, 0xc000
	ds_read_b128 v[160:163], v219
	ds_read_b128 v[164:167], v219 offset:1024
	ds_read_b128 v[178:181], v219 offset:2048
	ds_read_b128 v[182:185], v219 offset:3072
	ds_read_b128 v[186:189], v219 offset:4096
	ds_read_b128 v[198:201], v219 offset:5120
	ds_read_b128 v[202:205], v219 offset:6144
	ds_read_b128 v[220:223], v219 offset:7168
	global_load_lds_dwordx4 v[190:191], off
	v_lshl_add_u64 v[190:191], vcc, 0, v[174:175]
	s_add_i32 m0, s33, 0xe000
	s_nop 0
	global_load_lds_dwordx4 v[190:191], off
	s_waitcnt vmcnt(26)
	s_waitcnt lgkmcnt(0)
	s_barrier
	s_setprio 1
	s_waitcnt lgkmcnt(0)
	v_mfma_f32_16x16x32_bf16 v[124:127], v[128:131], v[160:163], 0
	v_mfma_f32_16x16x32_bf16 v[60:63], v[136:139], v[160:163], 0
	v_mfma_f32_16x16x32_bf16 v[116:119], v[128:131], v[178:181], 0
	v_mfma_f32_16x16x32_bf16 v[52:55], v[136:139], v[178:181], 0
	v_mfma_f32_16x16x32_bf16 v[108:111], v[128:131], v[186:189], 0
	v_mfma_f32_16x16x32_bf16 v[44:47], v[136:139], v[186:189], 0
	v_mfma_f32_16x16x32_bf16 v[100:103], v[128:131], v[202:205], 0
	v_mfma_f32_16x16x32_bf16 v[36:39], v[136:139], v[202:205], 0
	v_mfma_f32_16x16x32_bf16 v[124:127], v[132:135], v[164:167], v[124:127]
	v_mfma_f32_16x16x32_bf16 v[60:63], v[140:143], v[164:167], v[60:63]
	v_mfma_f32_16x16x32_bf16 v[116:119], v[132:135], v[182:185], v[116:119]
	v_mfma_f32_16x16x32_bf16 v[52:55], v[140:143], v[182:185], v[52:55]
	v_mfma_f32_16x16x32_bf16 v[108:111], v[132:135], v[198:201], v[108:111]
	v_mfma_f32_16x16x32_bf16 v[44:47], v[140:143], v[198:201], v[44:47]
	v_mfma_f32_16x16x32_bf16 v[100:103], v[132:135], v[220:223], v[100:103]
	v_mfma_f32_16x16x32_bf16 v[36:39], v[140:143], v[220:223], v[36:39]
	s_setprio 0
	s_setprio 1
	v_mfma_f32_16x16x32_bf16 v[120:123], v[144:147], v[160:163], 0
	v_mfma_f32_16x16x32_bf16 v[56:59], v[152:155], v[160:163], 0
	v_mfma_f32_16x16x32_bf16 v[112:115], v[144:147], v[178:181], 0
	v_mfma_f32_16x16x32_bf16 v[48:51], v[152:155], v[178:181], 0
	v_mfma_f32_16x16x32_bf16 v[104:107], v[144:147], v[186:189], 0
	v_mfma_f32_16x16x32_bf16 v[40:43], v[152:155], v[186:189], 0
	v_mfma_f32_16x16x32_bf16 v[96:99], v[144:147], v[202:205], 0
	v_mfma_f32_16x16x32_bf16 v[32:35], v[152:155], v[202:205], 0
	v_mfma_f32_16x16x32_bf16 v[120:123], v[148:151], v[164:167], v[120:123]
	v_mfma_f32_16x16x32_bf16 v[56:59], v[156:159], v[164:167], v[56:59]
	v_mfma_f32_16x16x32_bf16 v[112:115], v[148:151], v[182:185], v[112:115]
	v_mfma_f32_16x16x32_bf16 v[48:51], v[156:159], v[182:185], v[48:51]
	v_mfma_f32_16x16x32_bf16 v[104:107], v[148:151], v[198:201], v[104:107]
	v_mfma_f32_16x16x32_bf16 v[40:43], v[156:159], v[198:201], v[40:43]
	v_mfma_f32_16x16x32_bf16 v[96:99], v[148:151], v[220:223], v[96:99]
	v_mfma_f32_16x16x32_bf16 v[32:35], v[156:159], v[220:223], v[32:35]
	s_setprio 0
	s_barrier
	s_add_i32 s76, s76, s75
	v_lshl_add_u64 v[190:191], s[0:1], 0, v[192:193]
	s_mov_b32 m0, s76
	ds_read_b128 v[160:163], v219 offset:16384
	ds_read_b128 v[164:167], v219 offset:17408
	ds_read_b128 v[178:181], v219 offset:18432
	ds_read_b128 v[182:185], v219 offset:19456
	ds_read_b128 v[186:189], v219 offset:20480
	ds_read_b128 v[198:201], v219 offset:21504
	ds_read_b128 v[202:205], v219 offset:22528
	ds_read_b128 v[220:223], v219 offset:23552
	global_load_lds_dwordx4 v[190:191], off
	s_add_i32 m0, s76, 0x2000
	s_add_u32 s76, s0, 0x40000
	v_lshl_add_u64 v[194:195], s[0:1], 0, v[168:169]
	s_addc_u32 s77, s1, 0
	s_add_i32 s29, s29, s75
	global_load_lds_dwordx4 v[194:195], off
	v_lshl_add_u64 v[196:197], s[76:77], 0, v[192:193]
	s_mov_b32 m0, s29
	v_lshl_add_u64 v[224:225], s[78:79], 0, v[170:171]
	global_load_lds_dwordx4 v[196:197], off
	v_lshl_add_u64 v[196:197], s[76:77], 0, v[168:169]
	s_add_i32 m0, s29, 0x2000
	s_nop 0
	global_load_lds_dwordx4 v[196:197], off
	v_lshl_add_u64 v[196:197], s[78:79], 0, v[172:173]
	s_mov_b32 m0, s33
	s_nop 0
	global_load_lds_dwordx4 v[196:197], off
	s_mov_b32 m0, s62
	s_nop 0
	global_load_lds_dwordx4 v[224:225], off
	s_waitcnt vmcnt(26)
	s_waitcnt lgkmcnt(0)
	s_barrier
; #define PG8_STAGE(bufoff, gbase, voff) do { _Pragma("unroll") for (int _i = 0; _i < 2; ++_i) \
;         __builtin_amdgcn_global_load_lds((const unsigned*)((const char*)(gbase) + (voff)[_i]), (PG8_LAS unsigned*)(lds + (bufoff) + ldsw + _i * 8192), 16, 0, 0); } while (0)
; #define PG8_LDA(dst, b, h) do { _Pragma("unroll") for (int m = 0; m < 4; ++m) _Pragma("unroll") for (int k = 0; k < 2; ++k) dst[m][k] = *(const PG8_LAS bf16x8*)(lds + PG8_SA(b, h) + aoff + m * 2048 + k * 1024); } while (0)
; #define PG8_LDB(dst, b, h) do { _Pragma("unroll") for (int n = 0; n < 2; ++n) _Pragma("unroll") for (int k = 0; k < 2; ++k) dst[n][k] = *(const PG8_LAS bf16x8*)(lds + PG8_SB(b, h) + boff + n * 2048 + k * 1024); } while (0)
; #define PG8_MMA(ai, bj, At, Bt) do { __builtin_amdgcn_s_setprio(1); _Pragma("unroll") for (int m = 0; m < 4; ++m) _Pragma("unroll") for (int n = 0; n < 2; ++n) _Pragma("unroll") for (int k = 0; k < 2; ++k) \
;         acc[ai][bj][m][n] = __builtin_amdgcn_mfma_f32_16x16x32_bf16(Bt[n][k], At[m][k], acc[ai][bj][m][n], 0, 0, 0); __builtin_amdgcn_s_setprio(0); } while (0)
; #define PG8_WAIT_V(n) asm volatile("s_waitcnt vmcnt(" #n ")" ::: "memory")
; #define PG8_WAIT_L(n) asm volatile("s_waitcnt lgkmcnt(" #n ")" ::: "memory")
; #define PG8_BAR __builtin_amdgcn_s_barrier()
; #define PG8_SCHED __builtin_amdgcn_sched_barrier(0)
; template <class Epi, class Sched, bool ALIGN_EPI = false, bool SP2 = false>
; __device__ __forceinline__ void gemm_phase(PG8_LAS unsigned char* lds, const Gemm g, const Sched& S, const Epi& E, int wave_in) {
;     ...
;             PG8_LDA(At, 0, 1); PG8_STAGE(PG8_SB(0, 0), b2, voffB); PG8_STAGE(PG8_SB(0, 1), b2 + hstep, voffB); PG8_STAGE(PG8_SA(0, 0), a2, voffA);
;             PG8_WAIT_V(8); PG8_WAIT_L(0); PG8_BAR; PG8_MMA(1, 0, At, B0); PG8_MMA(1, 1, At, B1); PG8_BAR; PG8_SCHED;
;             PG8_LDB(B0, 1, 0); PG8_LDB(B1, 1, 1); PG8_SCHED; PG8_LDA(At, 1, 0); PG8_STAGE(PG8_SA(0, 1), a2 + hstep, voffA);
;             PG8_WAIT_V(8); PG8_WAIT_L(0); PG8_BAR; PG8_MMA(0, 0, At, B0); PG8_MMA(0, 1, At, B1); PG8_BAR; PG8_SCHED;
	s_setprio 1
	s_waitcnt lgkmcnt(0)
	v_mfma_f32_16x16x32_bf16 v[92:95], v[128:131], v[160:163], 0
	v_mfma_f32_16x16x32_bf16 v[28:31], v[136:139], v[160:163], 0
	v_mfma_f32_16x16x32_bf16 v[84:87], v[128:131], v[178:181], 0
	v_mfma_f32_16x16x32_bf16 v[20:23], v[136:139], v[178:181], 0
	v_mfma_f32_16x16x32_bf16 v[76:79], v[128:131], v[186:189], 0
	v_mfma_f32_16x16x32_bf16 v[12:15], v[136:139], v[186:189], 0
	v_mfma_f32_16x16x32_bf16 v[68:71], v[128:131], v[202:205], 0
	v_mfma_f32_16x16x32_bf16 v[4:7], v[136:139], v[202:205], 0
	v_mfma_f32_16x16x32_bf16 v[92:95], v[132:135], v[164:167], v[92:95]
	v_mfma_f32_16x16x32_bf16 v[28:31], v[140:143], v[164:167], v[28:31]
	v_mfma_f32_16x16x32_bf16 v[84:87], v[132:135], v[182:185], v[84:87]
	v_mfma_f32_16x16x32_bf16 v[20:23], v[140:143], v[182:185], v[20:23]
	v_mfma_f32_16x16x32_bf16 v[76:79], v[132:135], v[198:201], v[76:79]
	v_mfma_f32_16x16x32_bf16 v[12:15], v[140:143], v[198:201], v[12:15]
	v_mfma_f32_16x16x32_bf16 v[68:71], v[132:135], v[220:223], v[68:71]
	v_mfma_f32_16x16x32_bf16 v[4:7], v[140:143], v[220:223], v[4:7]
	s_setprio 0
	s_setprio 1
	v_mfma_f32_16x16x32_bf16 v[88:91], v[144:147], v[160:163], 0
	v_mfma_f32_16x16x32_bf16 v[24:27], v[152:155], v[160:163], 0
	v_mfma_f32_16x16x32_bf16 v[80:83], v[144:147], v[178:181], 0
	v_mfma_f32_16x16x32_bf16 v[16:19], v[152:155], v[178:181], 0
	v_mfma_f32_16x16x32_bf16 v[72:75], v[144:147], v[186:189], 0
	v_mfma_f32_16x16x32_bf16 v[8:11], v[152:155], v[186:189], 0
	v_mfma_f32_16x16x32_bf16 v[64:67], v[144:147], v[202:205], 0
	v_mfma_f32_16x16x32_bf16 v[0:3], v[152:155], v[202:205], 0
	v_mfma_f32_16x16x32_bf16 v[88:91], v[148:151], v[164:167], v[88:91]
	v_mfma_f32_16x16x32_bf16 v[24:27], v[156:159], v[164:167], v[24:27]
	v_mfma_f32_16x16x32_bf16 v[80:83], v[148:151], v[182:185], v[80:83]
	v_mfma_f32_16x16x32_bf16 v[16:19], v[156:159], v[182:185], v[16:19]
	v_mfma_f32_16x16x32_bf16 v[72:75], v[148:151], v[198:201], v[72:75]
	v_mfma_f32_16x16x32_bf16 v[8:11], v[156:159], v[198:201], v[8:11]
	v_mfma_f32_16x16x32_bf16 v[64:67], v[148:151], v[220:223], v[64:67]
	v_mfma_f32_16x16x32_bf16 v[0:3], v[156:159], v[220:223], v[0:3]
	s_setprio 0
	s_barrier
	s_add_i32 s29, s65, 0x100
	s_add_i32 s2, s52, 0x100
	v_add_u32_e32 v140, s29, v207
	v_add_u32_e32 v156, s2, v207
	ds_read_b128 v[128:131], v140
	ds_read_b128 v[132:135], v140 offset:1024
	ds_read_b128 v[136:139], v140 offset:2048
	ds_read_b128 v[140:143], v140 offset:3072
	ds_read_b128 v[144:147], v156
	ds_read_b128 v[148:151], v156 offset:1024
	ds_read_b128 v[152:155], v156 offset:2048
	ds_read_b128 v[156:159], v156 offset:3072
	s_add_u32 s76, s78, 0x40000
	s_addc_u32 s77, s79, 0
	s_mov_b32 m0, s63
	v_lshl_add_u64 v[226:227], s[76:77], 0, v[172:173]
	ds_read_b128 v[160:163], v219 offset:32768
	ds_read_b128 v[164:167], v219 offset:33792
	ds_read_b128 v[178:181], v219 offset:34816
	ds_read_b128 v[182:185], v219 offset:35840
	ds_read_b128 v[186:189], v219 offset:36864
	ds_read_b128 v[198:201], v219 offset:37888
	ds_read_b128 v[202:205], v219 offset:38912
	ds_read_b128 v[220:223], v219 offset:39936
	global_load_lds_dwordx4 v[226:227], off
	v_lshl_add_u64 v[226:227], s[76:77], 0, v[170:171]
	s_mov_b32 m0, s31
	s_nop 0
	global_load_lds_dwordx4 v[226:227], off
	s_waitcnt vmcnt(8)
	s_waitcnt lgkmcnt(0)
	s_barrier
	s_setprio 1
	s_waitcnt lgkmcnt(0)
	v_mfma_f32_16x16x32_bf16 v[124:127], v[128:131], v[160:163], v[124:127]
	v_mfma_f32_16x16x32_bf16 v[60:63], v[136:139], v[160:163], v[60:63]
	v_mfma_f32_16x16x32_bf16 v[116:119], v[128:131], v[178:181], v[116:119]
	v_mfma_f32_16x16x32_bf16 v[52:55], v[136:139], v[178:181], v[52:55]
	v_mfma_f32_16x16x32_bf16 v[108:111], v[128:131], v[186:189], v[108:111]
	v_mfma_f32_16x16x32_bf16 v[44:47], v[136:139], v[186:189], v[44:47]
	v_mfma_f32_16x16x32_bf16 v[100:103], v[128:131], v[202:205], v[100:103]
	v_mfma_f32_16x16x32_bf16 v[36:39], v[136:139], v[202:205], v[36:39]
	v_mfma_f32_16x16x32_bf16 v[124:127], v[132:135], v[164:167], v[124:127]
	v_mfma_f32_16x16x32_bf16 v[60:63], v[140:143], v[164:167], v[60:63]
	v_mfma_f32_16x16x32_bf16 v[116:119], v[132:135], v[182:185], v[116:119]
	v_mfma_f32_16x16x32_bf16 v[52:55], v[140:143], v[182:185], v[52:55]
	v_mfma_f32_16x16x32_bf16 v[108:111], v[132:135], v[198:201], v[108:111]
	v_mfma_f32_16x16x32_bf16 v[44:47], v[140:143], v[198:201], v[44:47]
	v_mfma_f32_16x16x32_bf16 v[100:103], v[132:135], v[220:223], v[100:103]
	v_mfma_f32_16x16x32_bf16 v[36:39], v[140:143], v[220:223], v[36:39]
	s_setprio 0
	s_setprio 1
	v_mfma_f32_16x16x32_bf16 v[120:123], v[144:147], v[160:163], v[120:123]
	v_mfma_f32_16x16x32_bf16 v[56:59], v[152:155], v[160:163], v[56:59]
	v_mfma_f32_16x16x32_bf16 v[112:115], v[144:147], v[178:181], v[112:115]
	v_mfma_f32_16x16x32_bf16 v[48:51], v[152:155], v[178:181], v[48:51]
	v_mfma_f32_16x16x32_bf16 v[104:107], v[144:147], v[186:189], v[104:107]
	v_mfma_f32_16x16x32_bf16 v[40:43], v[152:155], v[186:189], v[40:43]
	v_mfma_f32_16x16x32_bf16 v[96:99], v[144:147], v[202:205], v[96:99]
	v_mfma_f32_16x16x32_bf16 v[32:35], v[152:155], v[202:205], v[32:35]
	v_mfma_f32_16x16x32_bf16 v[120:123], v[148:151], v[164:167], v[120:123]
	v_mfma_f32_16x16x32_bf16 v[56:59], v[156:159], v[164:167], v[56:59]
	v_mfma_f32_16x16x32_bf16 v[112:115], v[148:151], v[182:185], v[112:115]
	v_mfma_f32_16x16x32_bf16 v[48:51], v[156:159], v[182:185], v[48:51]
	v_mfma_f32_16x16x32_bf16 v[104:107], v[148:151], v[198:201], v[104:107]
	v_mfma_f32_16x16x32_bf16 v[40:43], v[156:159], v[198:201], v[40:43]
	v_mfma_f32_16x16x32_bf16 v[96:99], v[148:151], v[220:223], v[96:99]
	v_mfma_f32_16x16x32_bf16 v[32:35], v[156:159], v[220:223], v[32:35]
	s_setprio 0
	s_barrier
; #define PG8_STAGE(bufoff, gbase, voff) do { _Pragma("unroll") for (int _i = 0; _i < 2; ++_i) \
;         __builtin_amdgcn_global_load_lds((const unsigned*)((const char*)(gbase) + (voff)[_i]), (PG8_LAS unsigned*)(lds + (bufoff) + ldsw + _i * 8192), 16, 0, 0); } while (0)
; #define PG8_LDA(dst, b, h) do { _Pragma("unroll") for (int m = 0; m < 4; ++m) _Pragma("unroll") for (int k = 0; k < 2; ++k) dst[m][k] = *(const PG8_LAS bf16x8*)(lds + PG8_SA(b, h) + aoff + m * 2048 + k * 1024); } while (0)
; #define PG8_LDB(dst, b, h) do { _Pragma("unroll") for (int n = 0; n < 2; ++n) _Pragma("unroll") for (int k = 0; k < 2; ++k) dst[n][k] = *(const PG8_LAS bf16x8*)(lds + PG8_SB(b, h) + boff + n * 2048 + k * 1024); } while (0)
; #define PG8_MMA(ai, bj, At, Bt) do { __builtin_amdgcn_s_setprio(1); _Pragma("unroll") for (int m = 0; m < 4; ++m) _Pragma("unroll") for (int n = 0; n < 2; ++n) _Pragma("unroll") for (int k = 0; k < 2; ++k) \
;         acc[ai][bj][m][n] = __builtin_amdgcn_mfma_f32_16x16x32_bf16(Bt[n][k], At[m][k], acc[ai][bj][m][n], 0, 0, 0); __builtin_amdgcn_s_setprio(0); } while (0)
; #define PG8_WAIT_V(n) asm volatile("s_waitcnt vmcnt(" #n ")" ::: "memory")
; #define PG8_WAIT_L(n) asm volatile("s_waitcnt lgkmcnt(" #n ")" ::: "memory")
; #define PG8_BAR __builtin_amdgcn_s_barrier()
; #define PG8_SCHED __builtin_amdgcn_sched_barrier(0)
; template <class Epi, class Sched, bool ALIGN_EPI = false, bool SP2 = false>
; __device__ __forceinline__ void gemm_phase(PG8_LAS unsigned char* lds, const Gemm g, const Sched& S, const Epi& E, int wave_in) {
;     ...
;         for (int t = 0; t < nt; t += 2) {
;     ...
;             PG8_LDB(B0, 1, 0); PG8_LDB(B1, 1, 1); PG8_SCHED; PG8_LDA(At, 1, 0); PG8_STAGE(PG8_SA(0, 1), a2 + hstep, voffA);
;             PG8_WAIT_V(8); PG8_WAIT_L(0); PG8_BAR; PG8_MMA(0, 0, At, B0); PG8_MMA(0, 1, At, B1); PG8_BAR; PG8_SCHED;
;             PG8_LDA(At, 1, 1); PG8_STAGE(PG8_SB(1, 0), b3, voffB); PG8_STAGE(PG8_SB(1, 1), b3 + hstep, voffB); PG8_STAGE(PG8_SA(1, 0), a3, voffA);
;             PG8_WAIT_V(8); PG8_WAIT_L(0); PG8_BAR; PG8_MMA(1, 0, At, B0); PG8_MMA(1, 1, At, B1); PG8_BAR; PG8_SCHED;
	s_add_i32 s29, s29, s75
	v_lshl_add_u64 v[190:191], v[190:191], 0, s[88:89]
	s_mov_b32 m0, s29
	ds_read_b128 v[160:163], v219 offset:49152
	ds_read_b128 v[164:167], v219 offset:50176
	ds_read_b128 v[178:181], v219 offset:51200
	ds_read_b128 v[182:185], v219 offset:52224
	ds_read_b128 v[186:189], v219 offset:53248
	ds_read_b128 v[198:201], v219 offset:54272
	ds_read_b128 v[202:205], v219 offset:55296
	ds_read_b128 v[220:223], v219 offset:56320
	global_load_lds_dwordx4 v[190:191], off
	s_add_i32 m0, s29, 0x2000
	s_add_u32 s0, s0, 0x40080
	v_lshl_add_u64 v[190:191], v[194:195], 0, s[88:89]
	s_addc_u32 s1, s1, 0
	s_add_i32 s2, s2, s75
	global_load_lds_dwordx4 v[190:191], off
	v_lshl_add_u64 v[190:191], s[0:1], 0, v[192:193]
	s_mov_b32 m0, s2
	s_nop 0
	global_load_lds_dwordx4 v[190:191], off
	v_lshl_add_u64 v[190:191], s[0:1], 0, v[168:169]
	s_add_i32 m0, s2, 0x2000
	s_nop 0
	global_load_lds_dwordx4 v[190:191], off
	v_lshl_add_u64 v[190:191], v[196:197], 0, s[88:89]
	s_mov_b32 m0, s9
	s_nop 0
	global_load_lds_dwordx4 v[190:191], off
	v_lshl_add_u64 v[190:191], v[224:225], 0, s[88:89]
	s_mov_b32 m0, s96
	s_nop 0
	global_load_lds_dwordx4 v[190:191], off
	s_waitcnt vmcnt(8)
	s_waitcnt lgkmcnt(0)
	s_barrier
	s_setprio 1
	s_waitcnt lgkmcnt(0)
	v_mfma_f32_16x16x32_bf16 v[92:95], v[128:131], v[160:163], v[92:95]
	v_mfma_f32_16x16x32_bf16 v[28:31], v[136:139], v[160:163], v[28:31]
	v_mfma_f32_16x16x32_bf16 v[84:87], v[128:131], v[178:181], v[84:87]
	v_mfma_f32_16x16x32_bf16 v[20:23], v[136:139], v[178:181], v[20:23]
	v_mfma_f32_16x16x32_bf16 v[76:79], v[128:131], v[186:189], v[76:79]
	v_mfma_f32_16x16x32_bf16 v[12:15], v[136:139], v[186:189], v[12:15]
	v_mfma_f32_16x16x32_bf16 v[68:71], v[128:131], v[202:205], v[68:71]
	v_mfma_f32_16x16x32_bf16 v[4:7], v[136:139], v[202:205], v[4:7]
	v_mfma_f32_16x16x32_bf16 v[92:95], v[132:135], v[164:167], v[92:95]
	v_mfma_f32_16x16x32_bf16 v[28:31], v[140:143], v[164:167], v[28:31]
	v_mfma_f32_16x16x32_bf16 v[84:87], v[132:135], v[182:185], v[84:87]
	v_mfma_f32_16x16x32_bf16 v[20:23], v[140:143], v[182:185], v[20:23]
	v_mfma_f32_16x16x32_bf16 v[76:79], v[132:135], v[198:201], v[76:79]
	v_mfma_f32_16x16x32_bf16 v[12:15], v[140:143], v[198:201], v[12:15]
	v_mfma_f32_16x16x32_bf16 v[68:71], v[132:135], v[220:223], v[68:71]
	v_mfma_f32_16x16x32_bf16 v[4:7], v[140:143], v[220:223], v[4:7]
	s_setprio 0
	s_setprio 1
	v_mfma_f32_16x16x32_bf16 v[88:91], v[144:147], v[160:163], v[88:91]
	v_mfma_f32_16x16x32_bf16 v[24:27], v[152:155], v[160:163], v[24:27]
	v_mfma_f32_16x16x32_bf16 v[80:83], v[144:147], v[178:181], v[80:83]
	v_mfma_f32_16x16x32_bf16 v[16:19], v[152:155], v[178:181], v[16:19]
	v_mfma_f32_16x16x32_bf16 v[72:75], v[144:147], v[186:189], v[72:75]
	v_mfma_f32_16x16x32_bf16 v[8:11], v[152:155], v[186:189], v[8:11]
	v_mfma_f32_16x16x32_bf16 v[64:67], v[144:147], v[202:205], v[64:67]
	v_mfma_f32_16x16x32_bf16 v[0:3], v[152:155], v[202:205], v[0:3]
	v_mfma_f32_16x16x32_bf16 v[88:91], v[148:151], v[164:167], v[88:91]
	v_mfma_f32_16x16x32_bf16 v[24:27], v[156:159], v[164:167], v[24:27]
	v_mfma_f32_16x16x32_bf16 v[80:83], v[148:151], v[182:185], v[80:83]
	v_mfma_f32_16x16x32_bf16 v[16:19], v[156:159], v[182:185], v[16:19]
	v_mfma_f32_16x16x32_bf16 v[72:75], v[148:151], v[198:201], v[72:75]
	v_mfma_f32_16x16x32_bf16 v[8:11], v[156:159], v[198:201], v[8:11]
	v_mfma_f32_16x16x32_bf16 v[64:67], v[148:151], v[220:223], v[64:67]
	v_mfma_f32_16x16x32_bf16 v[0:3], v[156:159], v[220:223], v[0:3]
	s_setprio 0
	s_barrier
	s_add_i32 s19, s19, 2
	s_add_u32 s81, s81, 0x100
	s_addc_u32 s18, s18, 0
	s_add_u32 vcc_lo, vcc_lo, 0x100
	s_addc_u32 vcc_hi, vcc_hi, 0
	s_cmp_gt_u32 s19, 13
	s_cbranch_scc1 .Lkexit_6
